# diff-attn loop: precomputed per-lane K/V load offsets with scalar base arithmetic and saddr loads (removes 64-bit VALU address math per tile)
# speedup vs baseline: 1.0091x; 1.0025x over previous
.LBB0_454:
	s_mul_i32 s4, s13, 0x2c00
	s_mul_hi_u32 s7, s12, 0x2c00
	s_add_i32 s7, s7, s4
	s_mul_i32 s4, s12, 0x2c00
	s_add_u32 s4, s38, s4
	s_addc_u32 s7, s39, s7
	s_add_u32 s8, s4, 0x1e74b200
	s_addc_u32 s9, s7, 0
	s_lshl_b32 s82, s5, 7
	s_add_u32 s4, s8, s82
	s_addc_u32 s7, s9, 0
	v_add_u32_e32 v146, s10, v170
	s_add_u32 s21, s4, 0x2400
	v_lshlrev_b32_e32 v2, 6, v146
	v_mov_b64_e32 v[0:1], s[8:9]
	s_addc_u32 s23, s7, 0
	v_lshrrev_b32_e32 v157, 6, v169
	v_and_b32_e32 v159, 15, v167
	v_mad_i64_i32 v[0:1], s[10:11], v2, s59, v[0:1]
	s_add_u32 s27, s4, 0x2600
	v_lshl_or_b32 v2, v157, 4, v159
	s_addc_u32 s28, s7, 0
	s_lshl_b32 s4, s5, 8
	v_mul_u32_u24_e32 v2, 0x1600, v2
	v_lshl_add_u64 v[0:1], v[0:1], 0, s[82:83]
	s_add_u32 s4, s8, s4
	v_bfe_u32 v45, v167, 4, 2
	v_lshlrev_b32_e32 v2, 1, v2
	v_mov_b32_e32 v3, v16
	s_addc_u32 s5, s9, 0
	v_lshlrev_b32_e32 v4, 4, v45
	v_mov_b32_e32 v5, v16
	v_lshl_add_u64 v[0:1], v[0:1], 0, v[2:3]
	s_add_u32 s24, s4, 0x2800
	v_lshl_add_u64 v[8:9], v[0:1], 0, v[4:5]
	s_addc_u32 s25, s5, 0
	s_mov_b64 s[0:1], 0x2000
	v_add_co_u32_e32 v10, vcc, s3, v8
	s_mov_b64 s[4:5], 0x2200
	v_lshl_add_u64 v[4:5], v[8:9], 0, s[0:1]
	v_addc_co_u32_e32 v11, vcc, 0, v9, vcc
	v_lshl_add_u64 v[12:13], v[8:9], 0, s[4:5]
	global_load_dwordx4 v[0:3], v[10:11], off
	s_nop 0
	global_load_dwordx4 v[4:7], v[4:5], off offset:64
	s_nop 0
	global_load_dwordx4 v[8:11], v[10:11], off offset:512
	s_nop 0
	global_load_dwordx4 v[18:21], v[12:13], off offset:64
	v_ashrrev_i32_e32 v12, 31, v167
	v_lshrrev_b32_e32 v12, 23, v12
	v_add_u32_e32 v12, v167, v12
	v_ashrrev_i32_e32 v48, 9, v12
	v_mul_i32_i24_e32 v12, 0x200, v48
	v_add_u32_e32 v30, 0x200, v167
	v_sub_u32_e32 v12, v167, v12
	v_ashrrev_i32_e32 v26, 31, v30
	v_ashrrev_i16_e32 v13, 15, v12
	v_lshrrev_b32_e32 v26, 23, v26
	v_lshrrev_b16_e32 v13, 13, v13
	v_add_u32_e32 v26, v30, v26
	v_add_u16_e32 v13, v12, v13
	v_ashrrev_i32_e32 v51, 9, v26
	v_ashrrev_i16_e32 v14, 3, v13
	v_and_b32_e32 v13, -8, v13
	v_mul_i32_i24_e32 v26, 0x200, v51
	v_sub_u16_e32 v12, v12, v13
	v_sub_u32_e32 v26, v30, v26
	v_bfe_i32 v50, v12, 0, 16
	v_add_u32_e32 v12, 0x1ff, v167
	s_movk_i32 s4, 0x3ff
	v_ashrrev_i16_e32 v27, 15, v26
	v_bfe_i32 v49, v14, 0, 16
	v_cmp_gt_u32_e64 s[4:5], s4, v12
	v_mov_b32_e32 v22, s28
	v_mov_b32_e32 v23, s23
	v_mov_b32_e32 v24, s27
	v_mov_b32_e32 v25, s21
	v_lshlrev_b32_e32 v148, 3, v50
	v_lshrrev_b16_e32 v27, 13, v27
	v_cndmask_b32_e64 v35, v22, v23, s[4:5]
	v_cndmask_b32_e64 v34, v24, v25, s[4:5]
	v_mul_hi_i32_i24_e32 v13, 0x2c00, v49
	v_mul_i32_i24_e32 v12, 0x2c00, v49
	v_ashrrev_i32_e32 v149, 31, v148
	v_add_u16_e32 v27, v26, v27
	v_lshl_add_u64 v[12:13], v[34:35], 0, v[12:13]
	v_lshlrev_b64 v[36:37], 1, v[148:149]
	v_ashrrev_i16_e32 v28, 3, v27
	v_and_b32_e32 v27, -8, v27
	v_lshl_add_u64 v[12:13], v[12:13], 0, v[36:37]
	v_sub_u16_e32 v26, v26, v27
	s_add_i32 s29, s6, s26
	global_load_dwordx4 v[12:15], v[12:13], off
	v_bfe_i32 v53, v26, 0, 16
	s_movk_i32 s6, 0xfc00
	v_bfe_i32 v52, v28, 0, 16
	v_cmp_lt_u32_e64 s[6:7], s6, v167
	v_lshlrev_b32_e32 v152, 3, v53
	v_ashrrev_i32_e32 v153, 31, v152
	v_cndmask_b32_e64 v39, v22, v23, s[6:7]
	v_cndmask_b32_e64 v38, v24, v25, s[6:7]
	v_mul_hi_i32_i24_e32 v23, 0x2c00, v52
	v_mul_i32_i24_e32 v22, 0x2c00, v52
	v_lshl_add_u64 v[22:23], v[38:39], 0, v[22:23]
	v_lshlrev_b64 v[40:41], 1, v[152:153]
	v_lshl_add_u64 v[22:23], v[22:23], 0, v[40:41]
	v_lshlrev_b32_e32 v28, 3, v167
	global_load_dwordx4 v[22:25], v[22:23], off
	v_ashrrev_i32_e32 v54, 4, v167
	v_mov_b64_e32 v[42:43], s[24:25]
	v_and_b32_e32 v44, 0x78, v28
	v_mad_i64_i32 v[26:27], s[8:9], v54, s59, v[42:43]
	v_lshlrev_b32_e32 v46, 1, v44
	v_mov_b32_e32 v47, v16
	v_ashrrev_i32_e32 v55, 4, v30
	v_lshl_add_u64 v[26:27], v[26:27], 0, v[46:47]
	v_mad_i64_i32 v[30:31], s[8:9], v55, s59, v[42:43]
	global_load_dwordx4 v[26:29], v[26:27], off
	v_lshl_add_u64 v[30:31], v[30:31], 0, v[46:47]
	global_load_dwordx4 v[30:33], v[30:31], off
	v_lshlrev_b32_e32 v48, 13, v48
	v_lshl_add_u32 v147, v49, 7, v48
	v_lshrrev_b32_e32 v48, 1, v49
	v_bitop3_b32 v48, v48, v50, 7 bitop3:0x6c
	v_lshlrev_b32_e32 v163, 4, v48
	v_add3_u32 v48, 0, v147, v163
	v_mul_lo_u32 v170, v54, s92
	v_mul_lo_u32 v172, v55, s92
	v_lshrrev_b32_e32 v17, 4, v167
	v_lshlrev_b32_e32 v160, 2, v45
	v_lshlrev_b32_e32 v154, 1, v44
	s_lshl_b32 s98, s20, 1
	s_lshl_b32 s99, s22, 1
	v_lshlrev_b32_e32 v252, 1, v148
	v_lshlrev_b32_e32 v253, 1, v152
	v_mad_u32_u24 v214, v49, s59, v252
	v_mad_u32_u24 v183, v52, s59, v253
	v_mad_u32_u24 v182, v54, s59, v154
	v_mad_u32_u24 v181, v55, s59, v154
	v_mad_u32_u24 v148, v49, s98, v252
	v_mad_u32_u24 v152, v52, s98, v253
	v_mad_u32_u24 v149, v54, s99, v154
	v_mad_u32_u24 v153, v55, s99, v154
	v_lshlrev_b32_e32 v178, 7, v159
	v_mov_b32_e32 v216, 0
	v_mov_b32_e32 v155, 0xf149f2ca
	v_mov_b32_e32 v217, 0xf149f2ca
	v_mov_b32_e32 v215, 0
	s_waitcnt vmcnt(0)
	ds_write_b128 v48, v[12:15]
	v_lshlrev_b32_e32 v12, 13, v51
	v_lshl_add_u32 v164, v52, 7, v12
	v_lshrrev_b32_e32 v12, 1, v52
	v_bitop3_b32 v12, v12, v53, 7 bitop3:0x6c
	v_lshlrev_b32_e32 v165, 4, v12
	v_add3_u32 v12, 0, v164, v165
	v_lshlrev_b32_e32 v14, 3, v169
	v_and_b32_e32 v15, 64, v191
	v_and_b32_e32 v169, 24, v14
	v_xor_b32_e32 v14, 16, v191
	v_add_u32_e32 v15, 64, v15
	v_cmp_lt_i32_e32 vcc, v14, v15
	ds_write_b128 v12, v[22:25]
	v_lshlrev_b32_e32 v12, 4, v167
	v_and_b32_e32 v171, 0xf0, v12
	v_add3_u32 v12, 0, v170, v171
	v_cndmask_b32_e32 v14, v191, v14, vcc
	v_lshlrev_b32_e32 v161, 2, v14
	v_xor_b32_e32 v14, 32, v191
	v_cmp_lt_i32_e32 vcc, v14, v15
	v_mov_b32_e32 v15, v16
	ds_write_b128 v12, v[26:29] offset:16384
	v_add3_u32 v12, 0, v172, v171
	ds_write_b128 v12, v[30:33] offset:16384
	v_add_u32_e32 v12, 64, v49
	v_mad_u64_u32 v[12:13], s[8:9], v12, s59, v[34:35]
	v_lshl_add_u64 v[12:13], v[12:13], 0, v[36:37]
	s_waitcnt lgkmcnt(0)
	s_barrier
	global_load_dwordx4 v[82:85], v[12:13], off
	v_add_u32_e32 v12, 64, v52
	v_mad_u64_u32 v[12:13], s[8:9], v12, s59, v[38:39]
	v_lshl_add_u64 v[12:13], v[12:13], 0, v[40:41]
	global_load_dwordx4 v[86:89], v[12:13], off
	v_add_u32_e32 v12, 64, v54
	v_mad_i64_i32 v[12:13], s[8:9], v12, s59, v[42:43]
	v_lshl_add_u64 v[12:13], v[12:13], 0, v[46:47]
	global_load_dwordx4 v[90:93], v[12:13], off
	v_add_u32_e32 v12, 64, v55
	v_mad_i64_i32 v[12:13], s[8:9], v12, s59, v[42:43]
	v_lshl_add_u64 v[12:13], v[12:13], 0, v[46:47]
	global_load_dwordx4 v[94:97], v[12:13], off
	v_bfe_u32 v12, v167, 1, 3
	v_cndmask_b32_e32 v14, v191, v14, vcc
	v_bfe_u32 v13, v167, 2, 2
	v_lshlrev_b32_e32 v162, 2, v14
	v_bitop3_b32 v14, v17, v12, 3 bitop3:0x6c
	v_bitop3_b32 v12, v45, v12, 4 bitop3:0x36
	v_mov_b32_e32 v17, v16
	v_lshlrev_b32_e32 v173, 4, v14
	v_lshlrev_b32_e32 v179, 4, v12
	v_or_b32_e32 v12, v160, v13
	v_mov_b32_e32 v14, v16
	v_mov_b64_e32 v[68:69], v[16:17]
	v_mov_b64_e32 v[72:73], v[16:17]
	v_mov_b64_e32 v[56:57], v[16:17]
	v_mov_b64_e32 v[52:53], v[16:17]
	v_mov_b64_e32 v[40:41], v[16:17]
	v_mov_b64_e32 v[36:37], v[16:17]
	v_mov_b64_e32 v[28:29], v[16:17]
	v_mov_b64_e32 v[24:25], v[16:17]
	v_mov_b64_e32 v[80:81], v[16:17]
	v_mov_b64_e32 v[76:77], v[16:17]
	v_mov_b64_e32 v[64:65], v[16:17]
	v_mov_b64_e32 v[60:61], v[16:17]
	v_mov_b64_e32 v[48:49], v[16:17]
	v_mov_b64_e32 v[44:45], v[16:17]
	v_mov_b64_e32 v[32:33], v[16:17]
	v_mul_u32_u24_e32 v180, 0x120, v12
	v_mov_b64_e32 v[66:67], v[14:15]
	v_mov_b64_e32 v[70:71], v[14:15]
	v_mov_b64_e32 v[54:55], v[14:15]
	v_mov_b64_e32 v[50:51], v[14:15]
	v_mov_b64_e32 v[38:39], v[14:15]
	v_mov_b64_e32 v[34:35], v[14:15]
	v_mov_b64_e32 v[26:27], v[14:15]
	v_mov_b64_e32 v[22:23], v[14:15]
	v_mov_b64_e32 v[78:79], v[14:15]
	v_mov_b64_e32 v[74:75], v[14:15]
	v_mov_b64_e32 v[62:63], v[14:15]
	v_mov_b64_e32 v[58:59], v[14:15]
	v_mov_b64_e32 v[46:47], v[14:15]
	v_mov_b64_e32 v[42:43], v[14:15]
	v_mov_b64_e32 v[30:31], v[14:15]
	v_mov_b64_e32 v[12:13], v[14:15]
	v_mov_b64_e32 v[14:15], v[16:17]
	v_add_u32_e32 v197, v178, v179
	v_add_u32_e32 v196, v178, v173
	ds_read_b128 v[220:223], v196
	ds_read_b128 v[224:227], v197
	ds_read_b128 v[228:231], v196 offset:2048
	ds_read_b128 v[232:235], v197 offset:2048
	ds_read_b128 v[236:239], v196 offset:4096
	ds_read_b128 v[240:243], v197 offset:4096
	ds_read_b128 v[244:247], v196 offset:6144
	ds_read_b128 v[248:251], v197 offset:6144

.LBB0_461:
	s_bitcmp1_b32 s31, 0
	s_cselect_b32 s98, 0x8800, 0
	s_add_i32 s30, s30, 2
	s_cmp_ge_u32 s30, s29
	s_waitcnt lgkmcnt(0)
	s_barrier
	v_add_u32_e32 v196, s98, v178
	v_add_u32_e32 v197, v196, v179
	v_add_u32_e32 v196, v196, v173
	ds_read_b128 v[220:223], v196
	ds_read_b128 v[224:227], v197
	ds_read_b128 v[228:231], v196 offset:2048
	ds_read_b128 v[232:235], v197 offset:2048
	ds_read_b128 v[236:239], v196 offset:4096
	ds_read_b128 v[240:243], v197 offset:4096
	ds_read_b128 v[244:247], v196 offset:6144
	ds_read_b128 v[248:251], v197 offset:6144
	s_cbranch_scc1 .LBB0_463
	s_cmp_lt_u32 s30, s26
	s_cbranch_scc0 .Lcl_iss_cached
	s_mul_i32 s62, s30, 0xb0000
	s_add_u32 s52, s21, s62
	s_addc_u32 s53, s23, 0
	s_add_u32 s60, s27, s62
	s_addc_u32 s61, s28, 0
	s_add_u32 s48, s24, s62
	s_addc_u32 s49, s25, 0
	s_waitcnt vmcnt(0)
	global_load_dwordx4 v[82:85], v214, s[52:53]
	global_load_dwordx4 v[86:89], v183, s[60:61]
	global_load_dwordx4 v[90:93], v182, s[48:49]
	global_load_dwordx4 v[94:97], v181, s[48:49]
	s_branch .LBB0_463
.Lcl_iss_cached:
	s_sub_i32 s62, s30, s26
	s_lshl_b32 s63, s22, 7
	s_mul_i32 s63, s62, s63
	s_lshl_b32 s53, s20, 7
	s_mul_i32 s62, s62, s53
	s_add_u32 s52, s14, s62
	s_addc_u32 s53, s15, 0
	s_add_u32 s60, s16, s62
	s_addc_u32 s61, s17, 0
	s_add_u32 s48, s18, s63
	s_addc_u32 s49, s19, 0
	s_waitcnt vmcnt(0)
	global_load_dwordx4 v[82:85], v148, s[52:53]
	global_load_dwordx4 v[86:89], v152, s[60:61]
	global_load_dwordx4 v[90:93], v149, s[48:49]
	global_load_dwordx4 v[94:97], v153, s[48:49]
.LBB0_463:
	v_add_f32_e32 v17, 0, v138
	v_add_f32_e32 v17, v139, v17
	v_add_f32_e32 v17, v140, v17
	v_add_f32_e32 v17, v141, v17
	v_add_f32_e32 v17, v130, v17
	v_add_f32_e32 v17, v131, v17
	v_add_f32_e32 v17, v132, v17
	v_add_f32_e32 v17, v133, v17
	v_add_f32_e32 v17, v122, v17
	v_add_f32_e32 v17, v123, v17
	v_add_f32_e32 v17, v124, v17
	v_add_f32_e32 v17, v125, v17
	v_add_f32_e32 v17, v114, v17
	v_add_f32_e32 v17, v115, v17
	v_add_f32_e32 v17, v116, v17
	v_add_f32_e32 v17, v117, v17
	v_cndmask_b32_e64 v98, v158, 1.0, s[10:11]
	v_fmac_f32_e32 v17, v216, v98
	v_add_f32_e32 v98, 0, v142
	v_add_f32_e32 v98, v143, v98
	v_add_f32_e32 v98, v144, v98
	v_add_f32_e32 v98, v145, v98
	v_add_f32_e32 v98, v134, v98
	v_add_f32_e32 v98, v135, v98
	v_add_f32_e32 v98, v136, v98
	v_add_f32_e32 v98, v137, v98
	v_add_f32_e32 v98, v126, v98
	v_add_f32_e32 v98, v127, v98
	v_add_f32_e32 v98, v128, v98
	v_add_f32_e32 v98, v129, v98
	v_add_f32_e32 v98, v118, v98
	v_add_f32_e32 v98, v119, v98
	v_add_f32_e32 v98, v120, v98
	v_add_f32_e32 v98, v121, v98
	v_cndmask_b32_e64 v99, v156, 1.0, s[8:9]
	v_fmac_f32_e32 v98, v215, v99
	s_cmp_lg_u32 s29, s31
	s_cbranch_scc0 .LBB0_465
	v_mov_b32_e32 v155, v218
	v_mov_b32_e32 v216, v17
	v_mov_b32_e32 v215, v98
	s_mov_b32 s30, s31
	s_branch .LBB0_455
